# scan: the odd half of each XCD-paired workgroup pair lags by a short sleep so its tile loads hit the L2 lines its partner just fetched
# baseline (speedup 1.0000x reference)
.Lscan_setup_done:
	s_waitcnt vmcnt(0) lgkmcnt(0)
	s_barrier
	s_bitcmp1_b32 s80, 0
	s_cbranch_scc0 .Lscan_nolag
	s_sleep 3
.Lscan_nolag:
	s_branch .LBB0_159
.LBB0_158:
	s_mov_b64 s[6:7], 0x60000
	s_add_i32 s10, s10, 1
	v_lshl_add_u64 v[38:39], v[38:39], 0, s[6:7]
	s_and_b32 s11, s10, 1
	s_cmp_lg_u32 s10, 63
	s_cbranch_scc0 .LBB0_163
